# instruction prefetch extended to the ada-flag wait (norm1 code) and the last barrier (final phase code)
# baseline (speedup 1.0000x reference)
; __device__ __forceinline__ void phase_norm1(const Params& p) {
;     const int tid = threadIdx.x, lane = tid & 63, wave = tid >> 6;
;     const int gw = blockIdx.x * NWAVES + wave, NGW = gridDim.x * NWAVES;
;     const float* ada = (const float*)(p.ws + WS_ADA);
;     f32x4 v[8], vn[8];
;     if (gw < MPROMPT) { const f32x4* xr = (const f32x4*)(p.in[I_XP] + (size_t)gw * DM) + lane;
; #pragma unroll
;         for (int j = 0; j < 8; ++j) v[j] = __builtin_nontemporal_load(xr + 64 * j); }
;     for (int row = gw; row < MPROMPT; row += NGW) {
;         const float* ar = ada + (size_t)(row >> 11) * NADA;
;         f32x4 sc[8], sh[8];
; #pragma unroll
;         for (int j = 0; j < 8; ++j) { const int col = 4 * lane + 256 * j; sc[j] = *(const f32x4*)(ar + DM + col); sh[j] = *(const f32x4*)(ar + col); }
;         if (row + NGW < MPROMPT) { const f32x4* xr = (const f32x4*)(p.in[I_XP] + (size_t)(row + NGW) * DM) + lane;
; #pragma unroll
;             for (int j = 0; j < 8; ++j) vn[j] = __builtin_nontemporal_load(xr + 64 * j); }
; __global__ void __launch_bounds__(NTHREADS, 2) fwd_megakernel(Params p) {
;     ...
;     if (threadIdx.x == 0) { unsigned* f = (unsigned*)(ws + WS_BAR) + ADA_FLAG; unsigned sp = 0;
;         while (__hip_atomic_load(f, __ATOMIC_RELAXED, __HIP_MEMORY_SCOPE_AGENT) < 48u) { __builtin_amdgcn_s_sleep(2); if (++sp > (1u << 20)) break; }
;         __builtin_amdgcn_fence(__ATOMIC_ACQUIRE, "agent"); asm volatile("s_waitcnt vmcnt(0)" ::: "memory"); }
;     __syncthreads();
.LBB0_165:
	s_waitcnt lgkmcnt(0)
	buffer_inv sc1
	s_waitcnt vmcnt(0)
.LBB0_166:
	s_or_b64 exec, exec, s[6:7]
	v_readfirstlane_b32 s98, v212
	s_lshr_b32 s98, s98, 6
	s_cmp_eq_u32 s98, 0
	s_cbranch_scc1 .Lipf_skip_1
	s_getpc_b64 s[100:101]
	v_mbcnt_lo_u32_b32 v0, -1, 0
	v_mbcnt_hi_u32_b32 v0, -1, v0
	v_lshlrev_b32_e32 v0, 4, v0
	s_lshl_b32 s98, s98, 10
	v_add_u32_e32 v0, s98, v0
	global_load_dwordx4 v[2:5], v0, s[100:101]
	s_add_u32 s100, s100, 0x1c00
	s_addc_u32 s101, s101, 0
	global_load_dwordx4 v[2:5], v0, s[100:101]
	s_add_u32 s100, s100, 0x1c00
	s_addc_u32 s101, s101, 0
	global_load_dwordx4 v[2:5], v0, s[100:101]
	s_add_u32 s100, s100, 0x1c00
	s_addc_u32 s101, s101, 0
	global_load_dwordx4 v[2:5], v0, s[100:101]
	s_add_u32 s100, s100, 0x1c00
	s_addc_u32 s101, s101, 0
	global_load_dwordx4 v[2:5], v0, s[100:101]
	s_add_u32 s100, s100, 0x1c00
	s_addc_u32 s101, s101, 0
	global_load_dwordx4 v[2:5], v0, s[100:101]
	s_waitcnt vmcnt(0)
.Lipf_skip_1:
	s_movk_i32 s3, 0x2000
	v_ashrrev_i32_e32 v211, 31, v210
	v_lshlrev_b32_e32 v214, 4, v184
	v_lshlrev_b32_e32 v218, 2, v184
	v_mbcnt_lo_u32_b32 v233, -1, 0
	s_waitcnt lgkmcnt(0)
	s_barrier
	v_cmp_gt_i32_e64 s[0:1], s3, v210
	s_mov_b64 s[8:9], exec
	s_nop 0
	v_writelane_b32 v255, s0, 8
	s_nop 1
	v_writelane_b32 v255, s1, 9
	s_and_b64 s[0:1], s[8:9], s[0:1]
	s_mov_b64 exec, s[0:1]
	s_cbranch_execz .LBB0_171
	v_readlane_b32 s12, v254, 1
	v_readlane_b32 s13, v254, 2
	v_lshlrev_b64 v[0:1], 13, v[210:211]
	v_readlane_b32 s14, v254, 3
	v_readlane_b32 s15, v254, 4
	s_mov_b64 s[4:5], s[12:13]
	v_mov_b32_e32 v129, 0
	v_lshl_add_u64 v[0:1], s[4:5], 0, v[0:1]
	v_mov_b32_e32 v215, v129
	v_lshl_add_u64 v[0:1], v[0:1], 0, v[214:215]
	global_load_dwordx4 v[60:63], v[0:1], off nt
	global_load_dwordx4 v[56:59], v[0:1], off offset:1024 nt
	global_load_dwordx4 v[52:55], v[0:1], off offset:2048 nt
	global_load_dwordx4 v[32:35], v[0:1], off offset:3072 nt
	v_add_co_u32_e32 v0, vcc, 0x1000, v0
	v_mbcnt_hi_u32_b32 v16, -1, v233
	s_nop 0
	v_addc_co_u32_e32 v1, vcc, 0, v1, vcc
	global_load_dwordx4 v[12:15], v[0:1], off nt
	global_load_dwordx4 v[8:11], v[0:1], off offset:1024 nt
	global_load_dwordx4 v[4:7], v[0:1], off offset:2048 nt
	s_nop 0
	global_load_dwordx4 v[0:3], v[0:1], off offset:3072 nt
	v_and_b32_e32 v17, 64, v16
	v_add_u32_e32 v17, 64, v17
	v_xor_b32_e32 v18, 1, v16
	v_cmp_lt_i32_e32 vcc, v18, v17
	v_lshlrev_b64 v[30:31], 12, v[210:211]
	v_lshl_or_b32 v30, v184, 3, v30
	v_cndmask_b32_e32 v18, v16, v18, vcc
	v_lshlrev_b32_e32 v150, 2, v18
	v_xor_b32_e32 v18, 2, v16
	v_cmp_lt_i32_e32 vcc, v18, v17
	v_lshl_add_u64 v[30:31], s[84:85], 0, v[30:31]
	s_mov_b64 s[0:1], 0xb900000
	v_cndmask_b32_e32 v18, v16, v18, vcc
	v_lshlrev_b32_e32 v151, 2, v18
	v_xor_b32_e32 v18, 4, v16
	v_cmp_lt_i32_e32 vcc, v18, v17
	v_lshl_add_u64 v[132:133], v[30:31], 0, s[0:1]
	v_readlane_b32 s0, v255, 6
	v_cndmask_b32_e32 v18, v16, v18, vcc
	v_lshlrev_b32_e32 v152, 2, v18
	v_xor_b32_e32 v18, 8, v16
	v_cmp_lt_i32_e32 vcc, v18, v17
	v_lshl_add_u64 v[130:131], s[4:5], 0, v[214:215]
	s_mov_b32 s4, s0
	v_cndmask_b32_e32 v18, v16, v18, vcc
	v_lshlrev_b32_e32 v153, 2, v18
	v_xor_b32_e32 v18, 16, v16
	v_cmp_lt_i32_e32 vcc, v18, v17
	v_readlane_b32 s1, v255, 7
	s_ashr_i32 s5, s0, 31
	v_cndmask_b32_e32 v18, v16, v18, vcc
	v_lshlrev_b32_e32 v154, 2, v18
	v_xor_b32_e32 v18, 32, v16
	v_cmp_lt_i32_e32 vcc, v18, v17
	s_mov_b32 s0, s4
	v_readlane_b32 s16, v254, 5
	v_cndmask_b32_e32 v16, v16, v18, vcc
	v_readlane_b32 s17, v254, 6
	v_lshlrev_b32_e32 v155, 2, v16
	v_or_b32_e32 v16, 0x100, v218
	v_or_b32_e32 v18, 0x200, v218
	v_or_b32_e32 v20, 0x300, v218
	v_or_b32_e32 v22, 0x400, v218
	v_or_b32_e32 v24, 0x500, v218
	v_or_b32_e32 v26, 0x600, v218
	v_or_b32_e32 v28, 0x700, v218
	v_writelane_b32 v255, s0, 6
	s_mov_b64 s[6:7], s[14:15]
	s_lshl_b64 s[10:11], s[4:5], 12
	v_writelane_b32 v255, s1, 7
	s_mov_b64 s[12:13], 0
	s_mov_b64 s[14:15], 0x2000
	v_lshlrev_b32_e32 v128, 2, v218
	v_lshlrev_b32_e32 v134, 2, v16
	v_lshlrev_b32_e32 v136, 2, v18
	v_lshlrev_b32_e32 v138, 2, v20
	v_lshlrev_b32_e32 v140, 2, v22
	v_lshlrev_b32_e32 v142, 2, v24
	v_lshlrev_b32_e32 v144, 2, v26
	v_lshlrev_b32_e32 v146, 2, v28
	s_movk_i32 s16, 0x1fff
	v_mov_b32_e32 v156, 0x358637bd
	s_mov_b32 s17, 0xf800000
	v_mov_b32_e32 v157, 0x260
	v_mov_b32_e32 v148, v210
	v_readlane_b32 s18, v254, 7
	v_readlane_b32 s19, v254, 8
	v_readlane_b32 s20, v254, 9
	v_readlane_b32 s21, v254, 10
	v_readlane_b32 s22, v254, 11
	v_readlane_b32 s23, v254, 12
	v_readlane_b32 s24, v254, 13
	v_readlane_b32 s25, v254, 14
	v_readlane_b32 s26, v254, 15
	v_readlane_b32 s27, v254, 16
	s_branch .LBB0_169

; __device__ __forceinline__ void phase_final(const Params& p) {
;     const int tid = threadIdx.x, lane = tid & 63, wave = tid >> 6;
;     const int gw = blockIdx.x * NWAVES + wave, NGW = gridDim.x * NWAVES;
;     const float* ada = (const float*)(p.ws + WS_ADA);
;     const bf16_t* Ob = (const bf16_t*)(p.ws + WS_FO); const float* Os = (const float*)(p.ws + WS_FOS2);
;     {
;         f32x4 x[8], xn[8]; u32x2 mb[8], mbn[8];
;         if (gw < MPROMPT) { const f32x4* xr = (const f32x4*)(p.out + (size_t)gw * DM) + lane; const u32x2* mr = (const u32x2*)(Ob + (size_t)gw * DM) + lane;
; #pragma unroll
;             for (int j = 0; j < 8; ++j) { x[j] = __builtin_nontemporal_load(xr + 64 * j); mb[j] = __builtin_nontemporal_load(mr + 64 * j); } }
;         for (int row = gw; row < MPROMPT; row += NGW) {
;             const float* ar = ada + (size_t)(row >> 11) * NADA;
;             f32x4 gt2[8];
; #pragma unroll
;             for (int j = 0; j < 8; ++j) { const int col = 4 * lane + 256 * j; gt2[j] = *(const f32x4*)(ar + 5 * DM + col); }
;             if (row + NGW < MPROMPT) { const f32x4* xr = (const f32x4*)(p.out + (size_t)(row + NGW) * DM) + lane; const u32x2* mr = (const u32x2*)(Ob + (size_t)(row + NGW) * DM) + lane;
; #pragma unroll
;                 for (int j = 0; j < 8; ++j) { xn[j] = __builtin_nontemporal_load(xr + 64 * j); mbn[j] = __builtin_nontemporal_load(mr + 64 * j); } }
.LBB0_1442:
	s_or_b64 exec, exec, s[2:3]
	v_readfirstlane_b32 s98, v212
	s_lshr_b32 s98, s98, 6
	s_cmp_eq_u32 s98, 0
	s_cbranch_scc1 .Lipf_skip_12
	s_getpc_b64 s[100:101]
	v_mbcnt_lo_u32_b32 v0, -1, 0
	v_mbcnt_hi_u32_b32 v0, -1, v0
	v_lshlrev_b32_e32 v0, 4, v0
	s_lshl_b32 s98, s98, 10
	s_sub_u32 s98, s98, 0x400
	v_add_u32_e32 v0, s98, v0
	s_cmp_gt_u32 s98, 4096
	s_cbranch_scc1 .Lipf_skip_12
	global_load_dwordx4 v[2:5], v0, s[100:101]
	s_waitcnt vmcnt(0)
.Lipf_skip_12:
	s_waitcnt lgkmcnt(0)
	s_barrier
	s_mov_b64 s[4:5], exec
	v_readlane_b32 s0, v255, 8
	v_readlane_b32 s1, v255, 9
	s_and_b64 s[0:1], s[4:5], s[0:1]
	v_readlane_b32 s24, v255, 6
	v_readlane_b32 s25, v255, 7
	s_mov_b64 exec, s[0:1]
	s_cbranch_execz .LBB0_1447
	v_readlane_b32 s8, v254, 33
	v_readlane_b32 s14, v254, 39
	v_readlane_b32 s15, v254, 40
	v_readlane_b32 s22, v254, 47
	v_readlane_b32 s23, v254, 48
	v_mov_b32_e32 v97, 0
	v_lshlrev_b64 v[0:1], 13, v[210:211]
	s_mov_b64 s[14:15], s[22:23]
	v_mov_b32_e32 v215, v97
	v_readlane_b32 s16, v254, 41
	v_lshl_add_u64 v[98:99], s[14:15], 0, v[0:1]
	v_lshl_add_u64 v[0:1], v[98:99], 0, v[214:215]
	s_movk_i32 s16, 0x1000
	v_lshlrev_b64 v[2:3], 12, v[210:211]
	v_add_co_u32_e32 v22, vcc, s16, v0
	v_lshl_add_u64 v[2:3], s[44:45], 0, v[2:3]
	v_mov_b32_e32 v223, v97
	v_addc_co_u32_e32 v23, vcc, 0, v1, vcc
	v_lshl_add_u64 v[20:21], v[2:3], 0, v[222:223]
	global_load_dwordx4 v[60:63], v[0:1], off nt
	global_load_dwordx4 v[40:43], v[0:1], off offset:1024 nt
	global_load_dwordx4 v[24:27], v[0:1], off offset:2048 nt
	global_load_dwordx4 v[16:19], v[0:1], off offset:3072 nt
	global_load_dwordx2 v[148:149], v[20:21], off nt
	global_load_dwordx2 v[146:147], v[20:21], off offset:512 nt
	global_load_dwordx2 v[144:145], v[20:21], off offset:1024 nt
	global_load_dwordx2 v[140:141], v[20:21], off offset:1536 nt
	global_load_dwordx4 v[12:15], v[22:23], off nt
	global_load_dwordx4 v[8:11], v[22:23], off offset:1024 nt
	global_load_dwordx4 v[4:7], v[22:23], off offset:2048 nt
	global_load_dwordx4 v[0:3], v[22:23], off offset:3072 nt
	global_load_dwordx2 v[142:143], v[20:21], off offset:2048 nt
	global_load_dwordx2 v[138:139], v[20:21], off offset:2560 nt
	global_load_dwordx2 v[136:137], v[20:21], off offset:3072 nt
	global_load_dwordx2 v[134:135], v[20:21], off offset:3584 nt
	v_mbcnt_hi_u32_b32 v20, -1, v233
	v_and_b32_e32 v21, 64, v20
	v_add_u32_e32 v21, 64, v21
	v_xor_b32_e32 v22, 1, v20
	v_cmp_lt_i32_e32 vcc, v22, v21
	v_add_u32_e32 v38, s24, v210
	v_ashrrev_i32_e32 v39, 31, v38
	v_cndmask_b32_e32 v22, v20, v22, vcc
	v_lshlrev_b32_e32 v150, 2, v22
	v_xor_b32_e32 v22, 2, v20
	v_cmp_lt_i32_e32 vcc, v22, v21
	v_lshlrev_b64 v[44:45], 12, v[38:39]
	v_or_b32_e32 v44, v44, v222
	v_cndmask_b32_e32 v22, v20, v22, vcc
	v_lshlrev_b32_e32 v151, 2, v22
	v_xor_b32_e32 v22, 4, v20
	v_cmp_lt_i32_e32 vcc, v22, v21
	v_readlane_b32 s9, v254, 34
	v_readlane_b32 s10, v254, 35
	v_cndmask_b32_e32 v22, v20, v22, vcc
	v_lshlrev_b32_e32 v152, 2, v22
	v_xor_b32_e32 v22, 8, v20
	v_cmp_lt_i32_e32 vcc, v22, v21
	v_readlane_b32 s11, v254, 36
	v_readlane_b32 s12, v254, 37
	v_cndmask_b32_e32 v22, v20, v22, vcc
	v_lshlrev_b32_e32 v153, 2, v22
	v_xor_b32_e32 v22, 16, v20
	v_cmp_lt_i32_e32 vcc, v22, v21
	v_readlane_b32 s13, v254, 38
	v_readlane_b32 s17, v254, 42
	v_cndmask_b32_e32 v22, v20, v22, vcc
	v_lshlrev_b32_e32 v154, 2, v22
	v_xor_b32_e32 v22, 32, v20
	v_cmp_lt_i32_e32 vcc, v22, v21
	v_readlane_b32 s18, v254, 43
	v_readlane_b32 s19, v254, 44
	v_cndmask_b32_e32 v20, v20, v22, vcc
	v_lshlrev_b32_e32 v155, 2, v20
	v_or_b32_e32 v20, 0x100, v218
	v_or_b32_e32 v22, 0x200, v218
	v_or_b32_e32 v28, 0x300, v218
	v_or_b32_e32 v30, 0x400, v218
	v_or_b32_e32 v32, 0x500, v218
	v_or_b32_e32 v34, 0x600, v218
	v_or_b32_e32 v36, 0x700, v218
	v_lshl_add_u64 v[44:45], s[84:85], 0, v[44:45]
	s_mov_b64 s[0:1], 0x6d00000
	s_ashr_i32 s25, s24, 31
	v_lshlrev_b64 v[38:39], 13, v[38:39]
	v_lshl_add_u64 v[100:101], v[44:45], 0, s[0:1]
	s_lshl_b64 s[8:9], s[24:25], 12
	s_lshl_b64 s[10:11], s[24:25], 13
	v_lshl_add_u64 v[102:103], s[14:15], 0, v[38:39]
	s_mov_b64 s[12:13], 0
	s_mov_b64 s[14:15], 0xa000
	v_lshlrev_b32_e32 v96, 2, v218
	v_lshlrev_b32_e32 v104, 2, v20
	v_lshlrev_b32_e32 v106, 2, v22
	v_lshlrev_b32_e32 v108, 2, v28
	v_lshlrev_b32_e32 v110, 2, v30
	v_lshlrev_b32_e32 v112, 2, v32
	v_lshlrev_b32_e32 v114, 2, v34
	v_lshlrev_b32_e32 v116, 2, v36
	s_movk_i32 s17, 0x2000
	s_movk_i32 s18, 0x1fff
	v_mov_b32_e32 v156, 0x358637bd
	s_mov_b32 s19, 0xf800000
	v_mov_b32_e32 v157, 0x260
	v_readlane_b32 s20, v254, 45
	v_readlane_b32 s21, v254, 46
	s_branch .LBB0_1445
